# v36 + SwiGLU GEMM epilogue: the eight rs[row] loads hoisted to the top of the epilogue, per-row-group vmcnt(0) waits (which also drained the previous store) removed
# speedup vs baseline: 1.0064x; 1.0046x over previous
; __device__ __forceinline__ u32x4 pack8(const f32x4 a, const f32x4 b) { u32x4 w; w.x = cvt_pk_bf16(a[0], a[1]); w.y = cvt_pk_bf16(a[2], a[3]); w.z = cvt_pk_bf16(b[0], b[1]); w.w = cvt_pk_bf16(b[2], b[3]); return w; }
;     __device__ __forceinline__ void operator()(const f32x4 (&acc)[2][2][4][2], const Unit& u, int wr, int wc, int fr, int fq) const {
;         const int row0 = u.pm * BM + wr * 64 + fr, col0 = u.pn * HALF + wc * 32 + 8 * fq;
; #pragma unroll
;         for (int ai = 0; ai < 2; ++ai)
; #pragma unroll
;             for (int m = 0; m < 4; ++m) { const int row = row0 + ai * HALF + m * 16; bf16_t* rowp = G + (size_t)row * 2816 + col0; f32x4 h[2];
;                 const float sc = rs[row];
; #pragma unroll
;                 for (int n = 0; n < 2; ++n) { const f32x4 g = acc[ai][0][m][n] * sc, up = acc[ai][1][m][n] * sc;
; #pragma unroll
;                     for (int j = 0; j < 4; ++j) { const float e = __builtin_amdgcn_exp2f(-1.4426950408889634f * g[j]); h[n][j] = g[j] * __builtin_amdgcn_rcpf(1.0f + e) * up[j]; } }
;                 *(u32x4*)rowp = pack8(h[0], h[1]); }
.LBB0_34:
	v_lshl_add_u32 v140, s86, 8, v151
	v_ashrrev_i32_e32 v141, 31, v140
	v_lshl_add_u64 v[144:145], v[140:141], 2, s[74:75]
	global_load_dword v150, v[144:145], off
	global_load_dword v155, v[144:145], off offset:64
	global_load_dword v227, v[144:145], off offset:128
	global_load_dword v248, v[144:145], off offset:192
	global_load_dword v249, v[144:145], off offset:512
	global_load_dword v250, v[144:145], off offset:576
	global_load_dword v251, v[144:145], off offset:640
	global_load_dword v253, v[144:145], off offset:704
	v_mov_b32_e32 v156, v122
	v_mov_b32_e32 v157, v126
	v_mov_b32_e32 v126, v123
	v_readlane_b32 s4, v252, 32
	v_lshl_or_b32 v146, s0, 7, v153
	v_readlane_b32 s5, v252, 33
	v_ashrrev_i32_e32 v147, 31, v146
	s_movk_i32 s0, 0x1600
	v_mov_b64_e32 v[142:143], s[4:5]
	v_mad_i64_i32 v[148:149], s[4:5], v140, s0, v[142:143]
	s_andn2_b64 vcc, exec, s[6:7]
	s_waitcnt vmcnt(0)
	v_pk_mul_f32 v[156:157], v[156:157], v[150:151] op_sel_hi:[1,0]
	s_nop 0
	v_mul_f32_e32 v122, 0xbfb8aa3b, v157
	v_exp_f32_e32 v122, v122
	s_nop 0
	v_add_f32_e32 v122, 1.0, v122
	v_rcp_f32_e32 v122, v122
	s_nop 0
	v_mul_f32_e32 v122, v157, v122
	v_mul_f32_e32 v141, v156, v122
	v_pk_mul_f32 v[122:123], v[126:127], v[150:151] op_sel_hi:[1,0]
	s_nop 0
	v_mul_f32_e32 v126, 0xbfb8aa3b, v123
	v_exp_f32_e32 v126, v126
	s_nop 0
	v_add_f32_e32 v126, 1.0, v126
	v_rcp_f32_e32 v126, v126
	s_nop 0
	v_mul_f32_e32 v123, v123, v126
	v_mul_f32_e32 v126, v122, v123
	v_mov_b32_e32 v122, v124
	v_mov_b32_e32 v123, v128
	v_pk_mul_f32 v[122:123], v[122:123], v[150:151] op_sel_hi:[1,0]
	v_mov_b32_e32 v128, v125
	v_mul_f32_e32 v124, 0xbfb8aa3b, v123
	v_exp_f32_e32 v124, v124
	s_nop 0
	v_add_f32_e32 v124, 1.0, v124
	v_rcp_f32_e32 v124, v124
	s_nop 0
	v_mul_f32_e32 v123, v123, v124
	v_mul_f32_e32 v124, v122, v123
	v_pk_mul_f32 v[122:123], v[128:129], v[150:151] op_sel_hi:[1,0]
	s_nop 0
	v_mul_f32_e32 v125, 0xbfb8aa3b, v123
	v_exp_f32_e32 v125, v125
	s_nop 0
	v_add_f32_e32 v125, 1.0, v125
	v_rcp_f32_e32 v125, v125
	s_nop 0
	v_mul_f32_e32 v123, v123, v125
	v_mul_f32_e32 v125, v122, v123
	v_mov_b32_e32 v122, v114
	v_mov_b32_e32 v123, v118
	v_pk_mul_f32 v[122:123], v[122:123], v[150:151] op_sel_hi:[1,0]
	v_mov_b32_e32 v118, v115
	v_mul_f32_e32 v114, 0xbfb8aa3b, v123
	v_exp_f32_e32 v114, v114
	s_nop 0
	v_add_f32_e32 v114, 1.0, v114
	v_rcp_f32_e32 v114, v114
	s_nop 0
	v_mul_f32_e32 v114, v123, v114
	v_mul_f32_e32 v122, v122, v114
	v_pk_mul_f32 v[114:115], v[118:119], v[150:151] op_sel_hi:[1,0]
	s_nop 0
	v_mul_f32_e32 v118, 0xbfb8aa3b, v115
	v_exp_f32_e32 v118, v118
	s_nop 0
	v_add_f32_e32 v118, 1.0, v118
	v_rcp_f32_e32 v118, v118
	s_nop 0
	v_mul_f32_e32 v115, v115, v118
	v_mul_f32_e32 v118, v114, v115
	v_mov_b32_e32 v114, v116
	v_mov_b32_e32 v115, v120
	v_pk_mul_f32 v[114:115], v[114:115], v[150:151] op_sel_hi:[1,0]
	v_mov_b32_e32 v120, v117
	v_mul_f32_e32 v116, 0xbfb8aa3b, v115
	v_exp_f32_e32 v116, v116
	s_nop 0
	v_add_f32_e32 v116, 1.0, v116
	v_rcp_f32_e32 v116, v116
	s_nop 0
	v_mul_f32_e32 v115, v115, v116
	v_mul_f32_e32 v119, v114, v115
	v_pk_mul_f32 v[114:115], v[120:121], v[150:151] op_sel_hi:[1,0]
	s_nop 0
	v_mul_f32_e32 v116, 0xbfb8aa3b, v115
	v_exp_f32_e32 v116, v116
	s_nop 0
	v_add_f32_e32 v116, 1.0, v116
	v_rcp_f32_e32 v116, v116
	s_nop 0
	v_mul_f32_e32 v115, v115, v116
	v_mul_f32_e32 v123, v114, v115
	v_lshlrev_b64 v[114:115], 1, v[146:147]
	v_lshl_add_u64 v[120:121], v[148:149], 0, v[114:115]
	v_cvt_pk_bf16_f32 v116, v141, v126
	v_cvt_pk_bf16_f32 v117, v124, v125
	v_cvt_pk_bf16_f32 v118, v122, v118
	v_cvt_pk_bf16_f32 v119, v119, v123
	global_store_dwordx4 v[120:121], v[116:119], off
	v_mov_b32_e32 v120, v106
	v_mov_b32_e32 v121, v110
	v_or_b32_e32 v118, 16, v140
	v_ashrrev_i32_e32 v119, 31, v118
	v_mad_i64_i32 v[116:117], s[4:5], v118, s0, v[142:143]
	v_lshl_add_u64 v[118:119], v[118:119], 2, s[74:75]
	v_mov_b32_e32 v110, v107
	v_mov_b32_e32 v118, v155
	v_pk_mul_f32 v[120:121], v[120:121], v[118:119] op_sel_hi:[1,0]
	s_nop 0
	v_mul_f32_e32 v106, 0xbfb8aa3b, v121
	v_exp_f32_e32 v106, v106
	s_nop 0
	v_add_f32_e32 v106, 1.0, v106
	v_rcp_f32_e32 v106, v106
	s_nop 0
	v_mul_f32_e32 v106, v121, v106
	v_mul_f32_e32 v119, v120, v106
	v_pk_mul_f32 v[106:107], v[110:111], v[118:119] op_sel_hi:[1,0]
	s_nop 0
	v_mul_f32_e32 v110, 0xbfb8aa3b, v107
	v_exp_f32_e32 v110, v110
	s_nop 0
	v_add_f32_e32 v110, 1.0, v110
	v_rcp_f32_e32 v110, v110
	s_nop 0
	v_mul_f32_e32 v107, v107, v110
	v_mul_f32_e32 v110, v106, v107
	v_mov_b32_e32 v106, v108
	v_mov_b32_e32 v107, v112
	v_pk_mul_f32 v[106:107], v[106:107], v[118:119] op_sel_hi:[1,0]
	v_mov_b32_e32 v112, v109
	v_mul_f32_e32 v108, 0xbfb8aa3b, v107
	v_exp_f32_e32 v108, v108
	s_nop 0
	v_add_f32_e32 v108, 1.0, v108
	v_rcp_f32_e32 v108, v108
	s_nop 0
	v_mul_f32_e32 v107, v107, v108
	v_mul_f32_e32 v108, v106, v107
	v_pk_mul_f32 v[106:107], v[112:113], v[118:119] op_sel_hi:[1,0]
	s_nop 0
	v_mul_f32_e32 v109, 0xbfb8aa3b, v107
	v_exp_f32_e32 v109, v109
	s_nop 0
	v_add_f32_e32 v109, 1.0, v109
	v_rcp_f32_e32 v109, v109
	s_nop 0
	v_mul_f32_e32 v107, v107, v109
	v_mul_f32_e32 v109, v106, v107
	v_mov_b32_e32 v106, v98
	v_mov_b32_e32 v107, v102
	v_pk_mul_f32 v[106:107], v[106:107], v[118:119] op_sel_hi:[1,0]
	v_mov_b32_e32 v102, v99
	v_mul_f32_e32 v98, 0xbfb8aa3b, v107
	v_exp_f32_e32 v98, v98
	s_nop 0
	v_add_f32_e32 v98, 1.0, v98
	v_rcp_f32_e32 v98, v98
	s_nop 0
	v_mul_f32_e32 v98, v107, v98
	v_mul_f32_e32 v106, v106, v98
	v_pk_mul_f32 v[98:99], v[102:103], v[118:119] op_sel_hi:[1,0]
	s_nop 0
	v_mul_f32_e32 v102, 0xbfb8aa3b, v99
	v_exp_f32_e32 v102, v102
	s_nop 0
	v_add_f32_e32 v102, 1.0, v102
	v_rcp_f32_e32 v102, v102
	s_nop 0
	v_mul_f32_e32 v99, v99, v102
; __device__ __forceinline__ u32x4 pack8(const f32x4 a, const f32x4 b) { u32x4 w; w.x = cvt_pk_bf16(a[0], a[1]); w.y = cvt_pk_bf16(a[2], a[3]); w.z = cvt_pk_bf16(b[0], b[1]); w.w = cvt_pk_bf16(b[2], b[3]); return w; }
;     __device__ __forceinline__ void operator()(const f32x4 (&acc)[2][2][4][2], const Unit& u, int wr, int wc, int fr, int fq) const {
;     ...
;             for (int m = 0; m < 4; ++m) { const int row = row0 + ai * HALF + m * 16; bf16_t* rowp = G + (size_t)row * 2816 + col0; f32x4 h[2];
;                 const float sc = rs[row];
; #pragma unroll
;                 for (int n = 0; n < 2; ++n) { const f32x4 g = acc[ai][0][m][n] * sc, up = acc[ai][1][m][n] * sc;
; #pragma unroll
;                     for (int j = 0; j < 4; ++j) { const float e = __builtin_amdgcn_exp2f(-1.4426950408889634f * g[j]); h[n][j] = g[j] * __builtin_amdgcn_rcpf(1.0f + e) * up[j]; } }
;                 *(u32x4*)rowp = pack8(h[0], h[1]); }
	v_mul_f32_e32 v107, v98, v99
	v_mov_b32_e32 v98, v100
	v_mov_b32_e32 v99, v104
	v_pk_mul_f32 v[98:99], v[98:99], v[118:119] op_sel_hi:[1,0]
	v_mov_b32_e32 v104, v101
	v_mul_f32_e32 v100, 0xbfb8aa3b, v99
	v_exp_f32_e32 v100, v100
	v_lshl_add_u64 v[102:103], v[116:117], 0, v[114:115]
	v_add_f32_e32 v100, 1.0, v100
	v_rcp_f32_e32 v100, v100
	s_nop 0
	v_mul_f32_e32 v99, v99, v100
	v_mul_f32_e32 v111, v98, v99
	v_pk_mul_f32 v[98:99], v[104:105], v[118:119] op_sel_hi:[1,0]
	s_nop 0
	v_mul_f32_e32 v100, 0xbfb8aa3b, v99
	v_exp_f32_e32 v100, v100
	s_nop 0
	v_add_f32_e32 v100, 1.0, v100
	v_rcp_f32_e32 v100, v100
	s_nop 0
	v_mul_f32_e32 v99, v99, v100
	v_mul_f32_e32 v101, v98, v99
	v_cvt_pk_bf16_f32 v98, v119, v110
	v_cvt_pk_bf16_f32 v99, v108, v109
	v_cvt_pk_bf16_f32 v100, v106, v107
	v_cvt_pk_bf16_f32 v101, v111, v101
	global_store_dwordx4 v[102:103], v[98:101], off
	v_mov_b32_e32 v102, v90
	v_mov_b32_e32 v103, v94
	v_or_b32_e32 v100, 32, v140
	v_ashrrev_i32_e32 v101, 31, v100
	v_mad_i64_i32 v[98:99], s[4:5], v100, s0, v[142:143]
	v_lshl_add_u64 v[100:101], v[100:101], 2, s[74:75]
	v_mov_b32_e32 v94, v91
	v_mov_b32_e32 v100, v227
	v_pk_mul_f32 v[102:103], v[102:103], v[100:101] op_sel_hi:[1,0]
	s_nop 0
	v_mul_f32_e32 v90, 0xbfb8aa3b, v103
	v_exp_f32_e32 v90, v90
	s_nop 0
	v_add_f32_e32 v90, 1.0, v90
	v_rcp_f32_e32 v90, v90
	s_nop 0
	v_mul_f32_e32 v90, v103, v90
	v_mul_f32_e32 v101, v102, v90
	v_pk_mul_f32 v[90:91], v[94:95], v[100:101] op_sel_hi:[1,0]
	s_nop 0
	v_mul_f32_e32 v94, 0xbfb8aa3b, v91
	v_exp_f32_e32 v94, v94
	s_nop 0
	v_add_f32_e32 v94, 1.0, v94
	v_rcp_f32_e32 v94, v94
	s_nop 0
	v_mul_f32_e32 v91, v91, v94
	v_mul_f32_e32 v94, v90, v91
	v_mov_b32_e32 v90, v92
	v_mov_b32_e32 v91, v96
	v_pk_mul_f32 v[90:91], v[90:91], v[100:101] op_sel_hi:[1,0]
	v_mov_b32_e32 v96, v93
	v_mul_f32_e32 v92, 0xbfb8aa3b, v91
	v_exp_f32_e32 v92, v92
	s_nop 0
	v_add_f32_e32 v92, 1.0, v92
	v_rcp_f32_e32 v92, v92
	s_nop 0
	v_mul_f32_e32 v91, v91, v92
	v_mul_f32_e32 v92, v90, v91
	v_pk_mul_f32 v[90:91], v[96:97], v[100:101] op_sel_hi:[1,0]
	s_nop 0
	v_mul_f32_e32 v93, 0xbfb8aa3b, v91
	v_exp_f32_e32 v93, v93
	s_nop 0
	v_add_f32_e32 v93, 1.0, v93
	v_rcp_f32_e32 v93, v93
	s_nop 0
	v_mul_f32_e32 v91, v91, v93
	v_mul_f32_e32 v93, v90, v91
	v_mov_b32_e32 v90, v82
	v_mov_b32_e32 v91, v86
	v_pk_mul_f32 v[90:91], v[90:91], v[100:101] op_sel_hi:[1,0]
	v_mov_b32_e32 v86, v83
	v_mul_f32_e32 v82, 0xbfb8aa3b, v91
	v_exp_f32_e32 v82, v82
	s_nop 0
	v_add_f32_e32 v82, 1.0, v82
	v_rcp_f32_e32 v82, v82
	s_nop 0
	v_mul_f32_e32 v82, v91, v82
	v_mul_f32_e32 v90, v90, v82
	v_pk_mul_f32 v[82:83], v[86:87], v[100:101] op_sel_hi:[1,0]
	s_nop 0
	v_mul_f32_e32 v86, 0xbfb8aa3b, v83
	v_exp_f32_e32 v86, v86
	s_nop 0
	v_add_f32_e32 v86, 1.0, v86
	v_rcp_f32_e32 v86, v86
	s_nop 0
	v_mul_f32_e32 v83, v83, v86
	v_mul_f32_e32 v91, v82, v83
	v_mov_b32_e32 v82, v84
	v_mov_b32_e32 v83, v88
	v_pk_mul_f32 v[82:83], v[82:83], v[100:101] op_sel_hi:[1,0]
	v_mov_b32_e32 v88, v85
	v_mul_f32_e32 v84, 0xbfb8aa3b, v83
	v_exp_f32_e32 v84, v84
	v_lshl_add_u64 v[86:87], v[98:99], 0, v[114:115]
	v_add_f32_e32 v84, 1.0, v84
	v_rcp_f32_e32 v84, v84
	s_nop 0
	v_mul_f32_e32 v83, v83, v84
	v_mul_f32_e32 v95, v82, v83
	v_pk_mul_f32 v[82:83], v[88:89], v[100:101] op_sel_hi:[1,0]
	s_nop 0
	v_mul_f32_e32 v84, 0xbfb8aa3b, v83
	v_exp_f32_e32 v84, v84
	s_nop 0
	v_add_f32_e32 v84, 1.0, v84
	v_rcp_f32_e32 v84, v84
	s_nop 0
	v_mul_f32_e32 v83, v83, v84
	v_mul_f32_e32 v85, v82, v83
	v_cvt_pk_bf16_f32 v82, v101, v94
	v_cvt_pk_bf16_f32 v83, v92, v93
	v_cvt_pk_bf16_f32 v84, v90, v91
	v_cvt_pk_bf16_f32 v85, v95, v85
	global_store_dwordx4 v[86:87], v[82:85], off
	v_mov_b32_e32 v87, v78
	v_mov_b32_e32 v78, v75
	v_or_b32_e32 v84, 48, v140
	v_ashrrev_i32_e32 v85, 31, v84
	v_mad_i64_i32 v[82:83], s[4:5], v84, s0, v[142:143]
	v_lshl_add_u64 v[84:85], v[84:85], 2, s[74:75]
	v_mov_b32_e32 v86, v74
	v_mov_b32_e32 v84, v248
	v_pk_mul_f32 v[78:79], v[78:79], v[84:85] op_sel_hi:[1,0]
	s_nop 0
	v_mul_f32_e32 v75, 0xbfb8aa3b, v79
	v_exp_f32_e32 v75, v75
	v_pk_mul_f32 v[86:87], v[86:87], v[84:85] op_sel_hi:[1,0]
	v_add_f32_e32 v75, 1.0, v75
	v_rcp_f32_e32 v75, v75
	v_mul_f32_e32 v74, 0xbfb8aa3b, v87
	v_exp_f32_e32 v74, v74
	v_mul_f32_e32 v75, v79, v75
	v_mul_f32_e32 v75, v78, v75
	v_mov_b32_e32 v78, v76
	v_mov_b32_e32 v79, v80
	v_pk_mul_f32 v[78:79], v[78:79], v[84:85] op_sel_hi:[1,0]
	v_mov_b32_e32 v80, v77
	v_mul_f32_e32 v76, 0xbfb8aa3b, v79
	v_exp_f32_e32 v76, v76
	v_add_f32_e32 v74, 1.0, v74
	v_rcp_f32_e32 v74, v74
	v_add_f32_e32 v76, 1.0, v76
	v_rcp_f32_e32 v76, v76
	v_mul_f32_e32 v74, v87, v74
	v_mul_f32_e32 v74, v86, v74
	v_mul_f32_e32 v76, v79, v76
	v_mul_f32_e32 v78, v78, v76
	v_pk_mul_f32 v[76:77], v[80:81], v[84:85] op_sel_hi:[1,0]
	s_nop 0
	v_mul_f32_e32 v79, 0xbfb8aa3b, v77
	v_exp_f32_e32 v79, v79
	s_nop 0
	v_add_f32_e32 v79, 1.0, v79
	v_rcp_f32_e32 v79, v79
	s_nop 0
	v_mul_f32_e32 v77, v77, v79
	v_mul_f32_e32 v79, v76, v77
	v_mov_b32_e32 v76, v66
	v_mov_b32_e32 v77, v70
	v_pk_mul_f32 v[76:77], v[76:77], v[84:85] op_sel_hi:[1,0]
	v_mov_b32_e32 v70, v67
	v_mul_f32_e32 v66, 0xbfb8aa3b, v77
	v_exp_f32_e32 v66, v66
	s_nop 0
	v_add_f32_e32 v66, 1.0, v66
	v_rcp_f32_e32 v66, v66
	s_nop 0
	v_mul_f32_e32 v66, v77, v66
	v_mul_f32_e32 v76, v76, v66
	v_pk_mul_f32 v[66:67], v[70:71], v[84:85] op_sel_hi:[1,0]
	s_nop 0
	v_mul_f32_e32 v70, 0xbfb8aa3b, v67
	v_exp_f32_e32 v70, v70
	s_nop 0
	v_add_f32_e32 v70, 1.0, v70
	v_rcp_f32_e32 v70, v70
	s_nop 0
	v_mul_f32_e32 v67, v67, v70
	v_mul_f32_e32 v77, v66, v67
	v_mov_b32_e32 v66, v68
	v_mov_b32_e32 v67, v72
	v_pk_mul_f32 v[66:67], v[66:67], v[84:85] op_sel_hi:[1,0]
	v_mov_b32_e32 v72, v69
; __device__ __forceinline__ u32x4 pack8(const f32x4 a, const f32x4 b) { u32x4 w; w.x = cvt_pk_bf16(a[0], a[1]); w.y = cvt_pk_bf16(a[2], a[3]); w.z = cvt_pk_bf16(b[0], b[1]); w.w = cvt_pk_bf16(b[2], b[3]); return w; }
;     __device__ __forceinline__ void operator()(const f32x4 (&acc)[2][2][4][2], const Unit& u, int wr, int wc, int fr, int fq) const {
;     ...
;             for (int m = 0; m < 4; ++m) { const int row = row0 + ai * HALF + m * 16; bf16_t* rowp = G + (size_t)row * 2816 + col0; f32x4 h[2];
;                 const float sc = rs[row];
; #pragma unroll
;                 for (int n = 0; n < 2; ++n) { const f32x4 g = acc[ai][0][m][n] * sc, up = acc[ai][1][m][n] * sc;
; #pragma unroll
;                     for (int j = 0; j < 4; ++j) { const float e = __builtin_amdgcn_exp2f(-1.4426950408889634f * g[j]); h[n][j] = g[j] * __builtin_amdgcn_rcpf(1.0f + e) * up[j]; } }
;                 *(u32x4*)rowp = pack8(h[0], h[1]); }
	v_mul_f32_e32 v68, 0xbfb8aa3b, v67
	v_exp_f32_e32 v68, v68
	v_lshl_add_u64 v[70:71], v[82:83], 0, v[114:115]
	v_add_f32_e32 v68, 1.0, v68
	v_rcp_f32_e32 v68, v68
	s_nop 0
	v_mul_f32_e32 v67, v67, v68
	v_mul_f32_e32 v80, v66, v67
	v_pk_mul_f32 v[66:67], v[72:73], v[84:85] op_sel_hi:[1,0]
	s_nop 0
	v_mul_f32_e32 v68, 0xbfb8aa3b, v67
	v_exp_f32_e32 v68, v68
	s_nop 0
	v_add_f32_e32 v68, 1.0, v68
	v_rcp_f32_e32 v68, v68
	s_nop 0
	v_mul_f32_e32 v67, v67, v68
	v_mul_f32_e32 v69, v66, v67
	v_cvt_pk_bf16_f32 v66, v74, v75
	v_cvt_pk_bf16_f32 v67, v78, v79
	v_cvt_pk_bf16_f32 v68, v76, v77
	v_cvt_pk_bf16_f32 v69, v80, v69
	global_store_dwordx4 v[70:71], v[66:69], off
	v_mov_b32_e32 v71, v62
	v_mov_b32_e32 v62, v59
	v_mov_b32_e32 v70, v58
	v_add_u32_e32 v66, 0x80, v140
	v_mad_i64_i32 v[66:67], s[4:5], v66, s0, v[142:143]
	v_mov_b32_e32 v68, v249
	v_pk_mul_f32 v[62:63], v[62:63], v[68:69] op_sel_hi:[1,0]
	s_nop 0
	v_mul_f32_e32 v59, 0xbfb8aa3b, v63
	v_exp_f32_e32 v59, v59
	v_pk_mul_f32 v[70:71], v[70:71], v[68:69] op_sel_hi:[1,0]
	v_add_f32_e32 v59, 1.0, v59
	v_rcp_f32_e32 v59, v59
	v_mul_f32_e32 v58, 0xbfb8aa3b, v71
	v_exp_f32_e32 v58, v58
	v_mul_f32_e32 v59, v63, v59
	v_mul_f32_e32 v59, v62, v59
	v_mov_b32_e32 v62, v60
	v_mov_b32_e32 v63, v64
	v_pk_mul_f32 v[62:63], v[62:63], v[68:69] op_sel_hi:[1,0]
	v_mov_b32_e32 v64, v61
	v_mul_f32_e32 v60, 0xbfb8aa3b, v63
	v_exp_f32_e32 v60, v60
	v_add_f32_e32 v58, 1.0, v58
	v_rcp_f32_e32 v58, v58
	v_add_f32_e32 v60, 1.0, v60
	v_rcp_f32_e32 v60, v60
	v_mul_f32_e32 v58, v71, v58
	v_mul_f32_e32 v58, v70, v58
	v_mul_f32_e32 v60, v63, v60
	v_mul_f32_e32 v62, v62, v60
	v_pk_mul_f32 v[60:61], v[64:65], v[68:69] op_sel_hi:[1,0]
	s_nop 0
	v_mul_f32_e32 v63, 0xbfb8aa3b, v61
	v_exp_f32_e32 v63, v63
	s_nop 0
	v_add_f32_e32 v63, 1.0, v63
	v_rcp_f32_e32 v63, v63
	s_nop 0
	v_mul_f32_e32 v61, v61, v63
	v_mul_f32_e32 v63, v60, v61
	v_mov_b32_e32 v60, v50
	v_mov_b32_e32 v61, v54
	v_pk_mul_f32 v[60:61], v[60:61], v[68:69] op_sel_hi:[1,0]
	v_mov_b32_e32 v54, v51
	v_mul_f32_e32 v50, 0xbfb8aa3b, v61
	v_exp_f32_e32 v50, v50
	s_nop 0
	v_add_f32_e32 v50, 1.0, v50
	v_rcp_f32_e32 v50, v50
	s_nop 0
	v_mul_f32_e32 v50, v61, v50
	v_mul_f32_e32 v60, v60, v50
	v_pk_mul_f32 v[50:51], v[54:55], v[68:69] op_sel_hi:[1,0]
	s_nop 0
	v_mul_f32_e32 v54, 0xbfb8aa3b, v51
	v_exp_f32_e32 v54, v54
	s_nop 0
	v_add_f32_e32 v54, 1.0, v54
	v_rcp_f32_e32 v54, v54
	s_nop 0
	v_mul_f32_e32 v51, v51, v54
	v_mul_f32_e32 v61, v50, v51
	v_mov_b32_e32 v50, v52
	v_mov_b32_e32 v51, v56
	v_pk_mul_f32 v[50:51], v[50:51], v[68:69] op_sel_hi:[1,0]
	v_mov_b32_e32 v56, v53
	v_mul_f32_e32 v52, 0xbfb8aa3b, v51
	v_exp_f32_e32 v52, v52
	v_lshl_add_u64 v[54:55], v[66:67], 0, v[114:115]
	v_add_f32_e32 v52, 1.0, v52
	v_rcp_f32_e32 v52, v52
	s_nop 0
	v_mul_f32_e32 v51, v51, v52
	v_mul_f32_e32 v64, v50, v51
	v_pk_mul_f32 v[50:51], v[56:57], v[68:69] op_sel_hi:[1,0]
	s_nop 0
	v_mul_f32_e32 v52, 0xbfb8aa3b, v51
	v_exp_f32_e32 v52, v52
	s_nop 0
	v_add_f32_e32 v52, 1.0, v52
	v_rcp_f32_e32 v52, v52
	s_nop 0
	v_mul_f32_e32 v51, v51, v52
	v_mul_f32_e32 v53, v50, v51
	v_cvt_pk_bf16_f32 v50, v58, v59
	v_cvt_pk_bf16_f32 v51, v62, v63
	v_cvt_pk_bf16_f32 v52, v60, v61
	v_cvt_pk_bf16_f32 v53, v64, v53
	global_store_dwordx4 v[54:55], v[50:53], off
	v_mov_b32_e32 v55, v46
	v_mov_b32_e32 v46, v43
	v_mov_b32_e32 v54, v42
	v_add_u32_e32 v50, 0x90, v140
	v_mad_i64_i32 v[50:51], s[4:5], v50, s0, v[142:143]
	v_mov_b32_e32 v52, v250
	v_pk_mul_f32 v[46:47], v[46:47], v[52:53] op_sel_hi:[1,0]
	s_nop 0
	v_mul_f32_e32 v43, 0xbfb8aa3b, v47
	v_exp_f32_e32 v43, v43
	v_pk_mul_f32 v[54:55], v[54:55], v[52:53] op_sel_hi:[1,0]
	v_add_f32_e32 v43, 1.0, v43
	v_rcp_f32_e32 v43, v43
	v_mul_f32_e32 v42, 0xbfb8aa3b, v55
	v_exp_f32_e32 v42, v42
	v_mul_f32_e32 v43, v47, v43
	v_mul_f32_e32 v43, v46, v43
	v_mov_b32_e32 v46, v44
	v_mov_b32_e32 v47, v48
	v_pk_mul_f32 v[46:47], v[46:47], v[52:53] op_sel_hi:[1,0]
	v_mov_b32_e32 v48, v45
	v_mul_f32_e32 v44, 0xbfb8aa3b, v47
	v_exp_f32_e32 v44, v44
	v_add_f32_e32 v42, 1.0, v42
	v_rcp_f32_e32 v42, v42
	v_add_f32_e32 v44, 1.0, v44
	v_rcp_f32_e32 v44, v44
	v_mul_f32_e32 v42, v55, v42
	v_mul_f32_e32 v42, v54, v42
	v_mul_f32_e32 v44, v47, v44
	v_mul_f32_e32 v46, v46, v44
	v_pk_mul_f32 v[44:45], v[48:49], v[52:53] op_sel_hi:[1,0]
	s_nop 0
	v_mul_f32_e32 v47, 0xbfb8aa3b, v45
	v_exp_f32_e32 v47, v47
	s_nop 0
	v_add_f32_e32 v47, 1.0, v47
	v_rcp_f32_e32 v47, v47
	s_nop 0
	v_mul_f32_e32 v45, v45, v47
	v_mul_f32_e32 v47, v44, v45
	v_mov_b32_e32 v44, v34
	v_mov_b32_e32 v45, v38
	v_pk_mul_f32 v[44:45], v[44:45], v[52:53] op_sel_hi:[1,0]
	v_mov_b32_e32 v38, v35
	v_mul_f32_e32 v34, 0xbfb8aa3b, v45
	v_exp_f32_e32 v34, v34
	s_nop 0
	v_add_f32_e32 v34, 1.0, v34
	v_rcp_f32_e32 v34, v34
	s_nop 0
	v_mul_f32_e32 v34, v45, v34
	v_mul_f32_e32 v44, v44, v34
	v_pk_mul_f32 v[34:35], v[38:39], v[52:53] op_sel_hi:[1,0]
	s_nop 0
	v_mul_f32_e32 v38, 0xbfb8aa3b, v35
	v_exp_f32_e32 v38, v38
	s_nop 0
	v_add_f32_e32 v38, 1.0, v38
	v_rcp_f32_e32 v38, v38
	s_nop 0
	v_mul_f32_e32 v35, v35, v38
	v_mul_f32_e32 v45, v34, v35
	v_mov_b32_e32 v34, v36
	v_mov_b32_e32 v35, v40
	v_pk_mul_f32 v[34:35], v[34:35], v[52:53] op_sel_hi:[1,0]
	v_mov_b32_e32 v40, v37
	v_mul_f32_e32 v36, 0xbfb8aa3b, v35
	v_exp_f32_e32 v36, v36
	v_lshl_add_u64 v[38:39], v[50:51], 0, v[114:115]
	v_add_f32_e32 v36, 1.0, v36
	v_rcp_f32_e32 v36, v36
	s_nop 0
	v_mul_f32_e32 v35, v35, v36
	v_mul_f32_e32 v48, v34, v35
	v_pk_mul_f32 v[34:35], v[40:41], v[52:53] op_sel_hi:[1,0]
	s_nop 0
	v_mul_f32_e32 v36, 0xbfb8aa3b, v35
	v_exp_f32_e32 v36, v36
	s_nop 0
	v_add_f32_e32 v36, 1.0, v36
; __device__ __forceinline__ u32x4 pack8(const f32x4 a, const f32x4 b) { u32x4 w; w.x = cvt_pk_bf16(a[0], a[1]); w.y = cvt_pk_bf16(a[2], a[3]); w.z = cvt_pk_bf16(b[0], b[1]); w.w = cvt_pk_bf16(b[2], b[3]); return w; }
; #define PG8_BAR __builtin_amdgcn_s_barrier()
;     __device__ __forceinline__ void operator()(const f32x4 (&acc)[2][2][4][2], const Unit& u, int wr, int wc, int fr, int fq) const {
;     ...
;             for (int m = 0; m < 4; ++m) { const int row = row0 + ai * HALF + m * 16; bf16_t* rowp = G + (size_t)row * 2816 + col0; f32x4 h[2];
;                 const float sc = rs[row];
; #pragma unroll
;                 for (int n = 0; n < 2; ++n) { const f32x4 g = acc[ai][0][m][n] * sc, up = acc[ai][1][m][n] * sc;
; #pragma unroll
;                     for (int j = 0; j < 4; ++j) { const float e = __builtin_amdgcn_exp2f(-1.4426950408889634f * g[j]); h[n][j] = g[j] * __builtin_amdgcn_rcpf(1.0f + e) * up[j]; } }
;                 *(u32x4*)rowp = pack8(h[0], h[1]); }
; template <class Epi, class Sched, bool ALIGN_EPI = false, bool SP2 = false>
; __device__ __forceinline__ void gemm_phase(PG8_LAS unsigned char* lds, const Gemm g, const Sched& S, const Epi& E, int wid_in) {
;     ...
;         if constexpr (!Epi::AFTER_DRAIN) { E(acc, cur, wr, wc, fr, fq); S.done(cur); }
;         if (!has_next) break;
; #pragma unroll
;         for (int a = 0; a < 2; ++a)
; #pragma unroll
;             for (int b = 0; b < 2; ++b)
; #pragma unroll
;                 for (int m = 0; m < 4; ++m)
; #pragma unroll
;                     for (int n = 0; n < 2; ++n) acc[a][b][m][n] = (f32x4){0.f, 0.f, 0.f, 0.f};
;         cur = nxt; cA = nA; cB = nB; ++ui;
;         if constexpr (ALIGN_EPI) { if (wr == 1) PG8_BAR; }
	v_rcp_f32_e32 v36, v36
	s_nop 0
	v_mul_f32_e32 v35, v35, v36
	v_mul_f32_e32 v37, v34, v35
	v_cvt_pk_bf16_f32 v34, v42, v43
	v_cvt_pk_bf16_f32 v35, v46, v47
	v_cvt_pk_bf16_f32 v36, v44, v45
	v_cvt_pk_bf16_f32 v37, v48, v37
	global_store_dwordx4 v[38:39], v[34:37], off
	v_mov_b32_e32 v39, v30
	v_mov_b32_e32 v30, v27
	v_mov_b32_e32 v38, v26
	v_add_u32_e32 v34, 0xa0, v140
	v_mad_i64_i32 v[34:35], s[4:5], v34, s0, v[142:143]
	v_mov_b32_e32 v36, v251
	v_pk_mul_f32 v[30:31], v[30:31], v[36:37] op_sel_hi:[1,0]
	s_nop 0
	v_mul_f32_e32 v27, 0xbfb8aa3b, v31
	v_exp_f32_e32 v27, v27
	v_pk_mul_f32 v[38:39], v[38:39], v[36:37] op_sel_hi:[1,0]
	v_add_f32_e32 v27, 1.0, v27
	v_rcp_f32_e32 v27, v27
	v_mul_f32_e32 v26, 0xbfb8aa3b, v39
	v_exp_f32_e32 v26, v26
	v_mul_f32_e32 v27, v31, v27
	v_mul_f32_e32 v27, v30, v27
	v_mov_b32_e32 v30, v28
	v_mov_b32_e32 v31, v32
	v_pk_mul_f32 v[30:31], v[30:31], v[36:37] op_sel_hi:[1,0]
	v_mov_b32_e32 v32, v29
	v_mul_f32_e32 v28, 0xbfb8aa3b, v31
	v_exp_f32_e32 v28, v28
	v_add_f32_e32 v26, 1.0, v26
	v_rcp_f32_e32 v26, v26
	v_add_f32_e32 v28, 1.0, v28
	v_rcp_f32_e32 v28, v28
	v_mul_f32_e32 v26, v39, v26
	v_mul_f32_e32 v26, v38, v26
	v_mul_f32_e32 v28, v31, v28
	v_mul_f32_e32 v30, v30, v28
	v_pk_mul_f32 v[28:29], v[32:33], v[36:37] op_sel_hi:[1,0]
	s_nop 0
	v_mul_f32_e32 v31, 0xbfb8aa3b, v29
	v_exp_f32_e32 v31, v31
	s_nop 0
	v_add_f32_e32 v31, 1.0, v31
	v_rcp_f32_e32 v31, v31
	s_nop 0
	v_mul_f32_e32 v29, v29, v31
	v_mul_f32_e32 v31, v28, v29
	v_mov_b32_e32 v28, v18
	v_mov_b32_e32 v29, v22
	v_pk_mul_f32 v[28:29], v[28:29], v[36:37] op_sel_hi:[1,0]
	v_mov_b32_e32 v22, v19
	v_mul_f32_e32 v18, 0xbfb8aa3b, v29
	v_exp_f32_e32 v18, v18
	s_nop 0
	v_add_f32_e32 v18, 1.0, v18
	v_rcp_f32_e32 v18, v18
	s_nop 0
	v_mul_f32_e32 v18, v29, v18
	v_mul_f32_e32 v28, v28, v18
	v_pk_mul_f32 v[18:19], v[22:23], v[36:37] op_sel_hi:[1,0]
	s_nop 0
	v_mul_f32_e32 v22, 0xbfb8aa3b, v19
	v_exp_f32_e32 v22, v22
	s_nop 0
	v_add_f32_e32 v22, 1.0, v22
	v_rcp_f32_e32 v22, v22
	s_nop 0
	v_mul_f32_e32 v19, v19, v22
	v_mul_f32_e32 v29, v18, v19
	v_mov_b32_e32 v18, v20
	v_mov_b32_e32 v19, v24
	v_pk_mul_f32 v[18:19], v[18:19], v[36:37] op_sel_hi:[1,0]
	v_mov_b32_e32 v24, v21
	v_mul_f32_e32 v20, 0xbfb8aa3b, v19
	v_exp_f32_e32 v20, v20
	v_lshl_add_u64 v[22:23], v[34:35], 0, v[114:115]
	v_add_f32_e32 v20, 1.0, v20
	v_rcp_f32_e32 v20, v20
	s_nop 0
	v_mul_f32_e32 v19, v19, v20
	v_mul_f32_e32 v32, v18, v19
	v_pk_mul_f32 v[18:19], v[24:25], v[36:37] op_sel_hi:[1,0]
	s_nop 0
	v_mul_f32_e32 v20, 0xbfb8aa3b, v19
	v_exp_f32_e32 v20, v20
	s_nop 0
	v_add_f32_e32 v20, 1.0, v20
	v_rcp_f32_e32 v20, v20
	s_nop 0
	v_mul_f32_e32 v19, v19, v20
	v_mul_f32_e32 v21, v18, v19
	v_cvt_pk_bf16_f32 v18, v26, v27
	v_cvt_pk_bf16_f32 v19, v30, v31
	v_cvt_pk_bf16_f32 v20, v28, v29
	v_cvt_pk_bf16_f32 v21, v32, v21
	global_store_dwordx4 v[22:23], v[18:21], off
	v_mov_b32_e32 v22, v10
	v_mov_b32_e32 v23, v14
	v_mov_b32_e32 v14, v11
	v_add_u32_e32 v18, 0xb0, v140
	v_mad_i64_i32 v[18:19], s[4:5], v18, s0, v[142:143]
	s_mov_b64 s[4:5], -1
	v_mov_b32_e32 v20, v253
	v_pk_mul_f32 v[22:23], v[22:23], v[20:21] op_sel_hi:[1,0]
	s_nop 0
	v_mul_f32_e32 v10, 0xbfb8aa3b, v23
	v_exp_f32_e32 v10, v10
	s_nop 0
	v_add_f32_e32 v10, 1.0, v10
	v_rcp_f32_e32 v10, v10
	s_nop 0
	v_mul_f32_e32 v10, v23, v10
	v_mul_f32_e32 v21, v22, v10
	v_pk_mul_f32 v[10:11], v[14:15], v[20:21] op_sel_hi:[1,0]
	s_nop 0
	v_mul_f32_e32 v14, 0xbfb8aa3b, v11
	v_exp_f32_e32 v14, v14
	s_nop 0
	v_add_f32_e32 v14, 1.0, v14
	v_rcp_f32_e32 v14, v14
	s_nop 0
	v_mul_f32_e32 v11, v11, v14
	v_mul_f32_e32 v14, v10, v11
	v_mov_b32_e32 v10, v12
	v_mov_b32_e32 v11, v16
	v_pk_mul_f32 v[10:11], v[10:11], v[20:21] op_sel_hi:[1,0]
	v_mov_b32_e32 v16, v13
	v_mul_f32_e32 v12, 0xbfb8aa3b, v11
	v_exp_f32_e32 v12, v12
	s_nop 0
	v_add_f32_e32 v12, 1.0, v12
	v_rcp_f32_e32 v12, v12
	s_nop 0
	v_mul_f32_e32 v11, v11, v12
	v_mul_f32_e32 v12, v10, v11
	v_pk_mul_f32 v[10:11], v[16:17], v[20:21] op_sel_hi:[1,0]
	s_nop 0
	v_mul_f32_e32 v13, 0xbfb8aa3b, v11
	v_exp_f32_e32 v13, v13
	s_nop 0
	v_add_f32_e32 v13, 1.0, v13
	v_rcp_f32_e32 v13, v13
	s_nop 0
	v_mul_f32_e32 v11, v11, v13
	v_mul_f32_e32 v13, v10, v11
	v_mov_b32_e32 v10, v2
	v_mov_b32_e32 v11, v6
	v_pk_mul_f32 v[10:11], v[10:11], v[20:21] op_sel_hi:[1,0]
	v_mov_b32_e32 v6, v3
	v_mul_f32_e32 v2, 0xbfb8aa3b, v11
	v_exp_f32_e32 v2, v2
	s_nop 0
	v_add_f32_e32 v2, 1.0, v2
	v_rcp_f32_e32 v2, v2
	s_nop 0
	v_mul_f32_e32 v2, v11, v2
	v_mul_f32_e32 v10, v10, v2
	v_pk_mul_f32 v[2:3], v[6:7], v[20:21] op_sel_hi:[1,0]
	s_nop 0
	v_mul_f32_e32 v6, 0xbfb8aa3b, v3
	v_exp_f32_e32 v6, v6
	s_nop 0
	v_add_f32_e32 v6, 1.0, v6
	v_rcp_f32_e32 v6, v6
	s_nop 0
	v_mul_f32_e32 v3, v3, v6
	v_mul_f32_e32 v11, v2, v3
	v_mov_b32_e32 v2, v4
	v_mov_b32_e32 v3, v8
	v_pk_mul_f32 v[2:3], v[2:3], v[20:21] op_sel_hi:[1,0]
	v_mov_b32_e32 v8, v5
	v_mul_f32_e32 v4, 0xbfb8aa3b, v3
	v_exp_f32_e32 v4, v4
	v_lshl_add_u64 v[6:7], v[18:19], 0, v[114:115]
	v_add_f32_e32 v4, 1.0, v4
	v_rcp_f32_e32 v4, v4
	s_nop 0
	v_mul_f32_e32 v3, v3, v4
	v_mul_f32_e32 v15, v2, v3
	v_pk_mul_f32 v[2:3], v[8:9], v[20:21] op_sel_hi:[1,0]
	s_nop 0
	v_mul_f32_e32 v4, 0xbfb8aa3b, v3
	v_exp_f32_e32 v4, v4
	s_nop 0
	v_add_f32_e32 v4, 1.0, v4
	v_rcp_f32_e32 v4, v4
	s_nop 0
	v_mul_f32_e32 v3, v3, v4
	v_mul_f32_e32 v5, v2, v3
	v_cvt_pk_bf16_f32 v2, v21, v14
	v_cvt_pk_bf16_f32 v3, v12, v13
	v_cvt_pk_bf16_f32 v4, v10, v11
	v_cvt_pk_bf16_f32 v5, v15, v5
	global_store_dwordx4 v[6:7], v[2:5], off
	s_cbranch_vccnz .LBB0_27
	s_andn2_b64 vcc, exec, s[34:35]
	s_cbranch_vccnz .LBB0_26
	s_barrier
	s_branch .LBB0_26
